# seam weight conversion queue + nt on f32 weight loads + write-through bf16 weight-copy stores
# baseline (speedup 1.0000x reference)
; __host__ __device__ __forceinline__ int blk_off(int r, int c) { const int rr = r & 127; return (r >> 7) * 8192 + (((rr >> 4) * 2 + (c >> 5)) * 512) + (rr & 15) * 32 + (c & 31); }
; __device__ __forceinline__ unsigned cvt_pk_bf16(float lo, float hi) { unsigned r; asm volatile("v_cvt_pk_bf16_f32 %0, %1, %2" : "=v"(r) : "v"(lo), "v"(hi)); return r; }
; __device__ __forceinline__ void titem_process(const TItem& d, const f32x4 (&v)[16], const float (&gg)[16], int lane) {
;     const int n0 = d.perm >> 1;
; #pragma unroll
;     for (int j = 0; j < 4; ++j) { const int n = n0 + 4 * (lane & 15) + j, nr = (d.perm & 1) ? win_row(n) : n;
;         const int w32 = nr & 31, nrs = (nr & 255 & ~31) + 16 * ((w32 >> 2) & 1) + 4 * (w32 >> 3) + (w32 & 3);
;         bf16* rowp = d.dst + (size_t)(nr >> 8) * (d.K >> 6) * (256 * 64);
; #pragma unroll
;         for (int h = 0; h < 2; ++h) { v4u o;
;             o.x = pg8::cvt_pk_bf16(v[8 * h + 0][j] * gg[8 * h + 0], v[8 * h + 1][j] * gg[8 * h + 1]); o.y = pg8::cvt_pk_bf16(v[8 * h + 2][j] * gg[8 * h + 2], v[8 * h + 3][j] * gg[8 * h + 3]);
;             o.z = pg8::cvt_pk_bf16(v[8 * h + 4][j] * gg[8 * h + 4], v[8 * h + 5][j] * gg[8 * h + 5]); o.w = pg8::cvt_pk_bf16(v[8 * h + 6][j] * gg[8 * h + 6], v[8 * h + 7][j] * gg[8 * h + 7]);
;             *(v4u*)(rowp + pg8::blk_off(nrs, 8 * (lane >> 4) + 32 * h)) = o; } }
.LBB0_101:
	v_and_b32_e32 v188, 0x60, v130
	v_lshlrev_b32_e32 v189, 2, v130
	s_ashr_i32 s4, s3, 6
	v_and_or_b32 v194, v189, 16, v188
	v_lshrrev_b32_e32 v188, 1, v130
	v_and_b32_e32 v189, 3, v130
	v_ashrrev_i32_e32 v191, 8, v130
	s_ashr_i32 s5, s4, 31
	v_and_or_b32 v190, v188, 12, v189
	v_ashrrev_i32_e32 v188, 31, v191
	s_lshl_b64 s[36:37], s[4:5], 15
	v_lshlrev_b32_e32 v130, 6, v130
	v_mul_lo_u32 v195, s36, v188
	s_lshr_b64 s[4:5], s[4:5], 17
	v_mov_b64_e32 v[188:189], s[0:1]
	v_and_b32_e32 v130, 0x2000, v130
	v_mul_i32_i24_e32 v196, s4, v191
	v_mad_u64_u32 v[192:193], s[4:5], s36, v191, v[188:189]
	v_lshl_or_b32 v130, v190, 5, v130
	s_waitcnt vmcnt(15)
	v_mul_f32_e32 v188, v162, v2
	s_waitcnt vmcnt(14)
	v_mul_f32_e32 v189, v161, v6
	v_lshlrev_b32_e32 v194, 6, v194
	v_cvt_pk_bf16_f32 v188, v188, v189
	s_waitcnt vmcnt(13)
	v_mul_f32_e32 v189, v164, v10
	s_waitcnt vmcnt(12)
	v_mul_f32_e32 v190, v163, v14
	v_or3_b32 v130, v130, v194, v179
	v_add3_u32 v193, v196, v193, v195
	v_cvt_pk_bf16_f32 v189, v189, v190
	s_waitcnt vmcnt(11)
	v_mul_f32_e32 v190, v166, v18
	s_waitcnt vmcnt(10)
	v_mul_f32_e32 v191, v165, v22
	v_lshlrev_b32_e32 v130, 1, v130
	v_cvt_pk_bf16_f32 v190, v190, v191
	s_waitcnt vmcnt(9)
	v_mul_f32_e32 v191, v168, v26
	v_lshl_add_u64 v[192:193], v[192:193], 0, v[130:131]
	s_waitcnt vmcnt(8)
	v_mul_f32_e32 v195, v167, v30
	v_cvt_pk_bf16_f32 v191, v191, v195
	global_store_dwordx4 v[192:193], v[188:191], off sc1
	s_waitcnt vmcnt(8)
	v_mul_f32_e32 v130, v171, v34
	s_andn2_b64 vcc, exec, s[38:39]
	s_waitcnt vmcnt(7)
	v_mul_f32_e32 v188, v170, v38
	v_cvt_pk_bf16_f32 v188, v130, v188
	s_waitcnt vmcnt(6)
	v_mul_f32_e32 v130, v173, v42
	s_waitcnt vmcnt(5)
	v_mul_f32_e32 v189, v172, v46
	v_cvt_pk_bf16_f32 v189, v130, v189
	s_waitcnt vmcnt(4)
	v_mul_f32_e32 v130, v175, v50
	s_waitcnt vmcnt(3)
	v_mul_f32_e32 v190, v174, v54
	v_cvt_pk_bf16_f32 v190, v130, v190
	s_waitcnt vmcnt(2)
	v_mul_f32_e32 v130, v178, v58
	s_waitcnt vmcnt(1)
	v_mul_f32_e32 v191, v176, v62
	v_cvt_pk_bf16_f32 v191, v130, v191
	v_cndmask_b32_e64 v130, 0, 1, s[38:39]
	v_cmp_ne_u32_e64 s[4:5], 1, v130
	v_add_u32_e32 v130, 1, v187
	global_store_dwordx4 v[192:193], v[188:191], off offset:1024 sc1
	s_cbranch_vccnz .LBB0_107
	v_cmp_gt_i32_e32 vcc, s52, v187
	s_and_saveexec_b64 s[38:39], vcc
	s_xor_b64 s[38:39], exec, s[38:39]
	v_lshlrev_b32_e32 v188, 2, v130
	v_lshrrev_b32_e32 v189, 1, v130
	v_and_b32_e32 v188, 0x80, v188
	v_and_b32_e32 v189, 0x60, v189
	v_and_b32_e32 v130, 0xffffff1f, v130
	v_or3_b32 v130, v188, v130, v189
	s_andn2_saveexec_b64 s[38:39], s[38:39]
	v_cmp_lt_u32_e32 vcc, s54, v130
	s_nop 1
	v_cndmask_b32_e32 v188, v180, v181, vcc
	v_add_lshl_u32 v188, v188, v130, 1
	v_and_b32_e32 v188, 0xffffff00, v188
	v_cndmask_b32_e32 v189, 0, v182, vcc
	v_and_b32_e32 v130, 0x7f, v130
	v_or3_b32 v130, v188, v189, v130
	v_add_u32_e32 v130, 0x1000, v130
	s_or_b64 exec, exec, s[38:39]
.LBB0_107:
	s_nop 0
	v_and_b32_e32 v188, 0x60, v130
	v_lshlrev_b32_e32 v189, 2, v130
	v_and_or_b32 v194, v189, 16, v188
	v_lshrrev_b32_e32 v188, 1, v130
	v_and_b32_e32 v189, 3, v130
	v_ashrrev_i32_e32 v191, 8, v130
	v_and_or_b32 v190, v188, 12, v189
	v_ashrrev_i32_e32 v188, 31, v191
	v_lshlrev_b32_e32 v130, 6, v130
	v_mul_lo_u32 v195, s36, v188
	v_mov_b64_e32 v[188:189], s[0:1]
	v_and_b32_e32 v130, 0x2000, v130
	v_mad_u64_u32 v[192:193], s[38:39], s36, v191, v[188:189]
	v_lshl_or_b32 v130, v190, 5, v130
	v_mul_f32_e32 v188, v162, v3
	v_mul_f32_e32 v189, v161, v7
	v_lshlrev_b32_e32 v194, 6, v194
	v_mul_i32_i24_e32 v196, s37, v191
	v_cvt_pk_bf16_f32 v188, v188, v189
	v_mul_f32_e32 v189, v164, v11
	v_mul_f32_e32 v190, v163, v15
	v_or3_b32 v130, v130, v194, v179
	v_add3_u32 v193, v196, v193, v195
	v_cvt_pk_bf16_f32 v189, v189, v190
	v_mul_f32_e32 v190, v166, v19
	v_mul_f32_e32 v191, v165, v23
	v_lshlrev_b32_e32 v130, 1, v130
	v_cvt_pk_bf16_f32 v190, v190, v191
	v_mul_f32_e32 v191, v168, v27
	v_lshl_add_u64 v[192:193], v[192:193], 0, v[130:131]
	v_mul_f32_e32 v195, v167, v31
	v_cvt_pk_bf16_f32 v191, v191, v195
	global_store_dwordx4 v[192:193], v[188:191], off sc1
	v_mul_f32_e32 v130, v171, v35
	s_and_b64 vcc, exec, s[4:5]
	v_mul_f32_e32 v188, v170, v39
	v_cvt_pk_bf16_f32 v188, v130, v188
	v_mul_f32_e32 v130, v173, v43
	v_mul_f32_e32 v189, v172, v47
	v_cvt_pk_bf16_f32 v189, v130, v189
	v_mul_f32_e32 v130, v175, v51
	v_mul_f32_e32 v190, v174, v55
	v_cvt_pk_bf16_f32 v190, v130, v190
	v_mul_f32_e32 v130, v178, v59
	v_mul_f32_e32 v191, v176, v63
	v_cvt_pk_bf16_f32 v191, v130, v191
	v_add_u32_e32 v130, 2, v187
	global_store_dwordx4 v[192:193], v[188:191], off offset:1024 sc1
	s_cbranch_vccnz .LBB0_113
	v_cmp_gt_i32_e32 vcc, s55, v187
	s_and_saveexec_b64 s[38:39], vcc
	s_xor_b64 s[38:39], exec, s[38:39]
	v_lshlrev_b32_e32 v188, 2, v130
	v_lshrrev_b32_e32 v189, 1, v130
	v_and_b32_e32 v188, 0x80, v188
	v_and_b32_e32 v189, 0x60, v189
	v_and_b32_e32 v130, 0xffffff1f, v130
	v_or3_b32 v130, v188, v130, v189
	s_andn2_saveexec_b64 s[38:39], s[38:39]
	v_cmp_lt_u32_e32 vcc, s54, v130
	s_nop 1
	v_cndmask_b32_e32 v188, v180, v181, vcc
	v_add_lshl_u32 v188, v188, v130, 1
	v_and_b32_e32 v188, 0xffffff00, v188
	v_cndmask_b32_e32 v189, 0, v182, vcc
	v_and_b32_e32 v130, 0x7f, v130
	v_or3_b32 v130, v188, v189, v130
	v_add_u32_e32 v130, 0x1000, v130
	s_or_b64 exec, exec, s[38:39]
; __host__ __device__ __forceinline__ int blk_off(int r, int c) { const int rr = r & 127; return (r >> 7) * 8192 + (((rr >> 4) * 2 + (c >> 5)) * 512) + (rr & 15) * 32 + (c & 31); }
; __device__ __forceinline__ unsigned cvt_pk_bf16(float lo, float hi) { unsigned r; asm volatile("v_cvt_pk_bf16_f32 %0, %1, %2" : "=v"(r) : "v"(lo), "v"(hi)); return r; }
; __device__ __forceinline__ void titem_process(const TItem& d, const f32x4 (&v)[16], const float (&gg)[16], int lane) {
;     const int n0 = d.perm >> 1;
; #pragma unroll
;     for (int j = 0; j < 4; ++j) { const int n = n0 + 4 * (lane & 15) + j, nr = (d.perm & 1) ? win_row(n) : n;
;         const int w32 = nr & 31, nrs = (nr & 255 & ~31) + 16 * ((w32 >> 2) & 1) + 4 * (w32 >> 3) + (w32 & 3);
;         bf16* rowp = d.dst + (size_t)(nr >> 8) * (d.K >> 6) * (256 * 64);
; #pragma unroll
;         for (int h = 0; h < 2; ++h) { v4u o;
;             o.x = pg8::cvt_pk_bf16(v[8 * h + 0][j] * gg[8 * h + 0], v[8 * h + 1][j] * gg[8 * h + 1]); o.y = pg8::cvt_pk_bf16(v[8 * h + 2][j] * gg[8 * h + 2], v[8 * h + 3][j] * gg[8 * h + 3]);
;             o.z = pg8::cvt_pk_bf16(v[8 * h + 4][j] * gg[8 * h + 4], v[8 * h + 5][j] * gg[8 * h + 5]); o.w = pg8::cvt_pk_bf16(v[8 * h + 6][j] * gg[8 * h + 6], v[8 * h + 7][j] * gg[8 * h + 7]);
;             *(v4u*)(rowp + pg8::blk_off(nrs, 8 * (lane >> 4) + 32 * h)) = o; } }
.LBB0_113:
	s_nop 0
	v_and_b32_e32 v188, 0x60, v130
	v_lshlrev_b32_e32 v189, 2, v130
	v_and_or_b32 v194, v189, 16, v188
	v_lshrrev_b32_e32 v188, 1, v130
	v_and_b32_e32 v189, 3, v130
	v_ashrrev_i32_e32 v191, 8, v130
	v_and_or_b32 v190, v188, 12, v189
	v_ashrrev_i32_e32 v188, 31, v191
	v_lshlrev_b32_e32 v130, 6, v130
	v_mul_lo_u32 v195, s36, v188
	v_mov_b64_e32 v[188:189], s[0:1]
	v_and_b32_e32 v130, 0x2000, v130
	v_mad_u64_u32 v[192:193], s[38:39], s36, v191, v[188:189]
	v_lshl_or_b32 v130, v190, 5, v130
	v_mul_f32_e32 v188, v162, v4
	v_mul_f32_e32 v189, v161, v8
	v_lshlrev_b32_e32 v194, 6, v194
	v_mul_i32_i24_e32 v196, s37, v191
	v_cvt_pk_bf16_f32 v188, v188, v189
	v_mul_f32_e32 v189, v164, v12
	v_mul_f32_e32 v190, v163, v16
	v_or3_b32 v130, v130, v194, v179
	v_add3_u32 v193, v196, v193, v195
	v_cvt_pk_bf16_f32 v189, v189, v190
	v_mul_f32_e32 v190, v166, v20
	v_mul_f32_e32 v191, v165, v24
	v_lshlrev_b32_e32 v130, 1, v130
	v_cvt_pk_bf16_f32 v190, v190, v191
	v_mul_f32_e32 v191, v168, v28
	v_lshl_add_u64 v[192:193], v[192:193], 0, v[130:131]
	v_mul_f32_e32 v195, v167, v32
	v_cvt_pk_bf16_f32 v191, v191, v195
	global_store_dwordx4 v[192:193], v[188:191], off sc1
	v_mul_f32_e32 v130, v171, v36
	s_and_b64 vcc, exec, s[4:5]
	v_mul_f32_e32 v188, v170, v40
	v_cvt_pk_bf16_f32 v188, v130, v188
	v_mul_f32_e32 v130, v173, v44
	v_mul_f32_e32 v189, v172, v48
	v_cvt_pk_bf16_f32 v189, v130, v189
	v_mul_f32_e32 v130, v175, v52
	v_mul_f32_e32 v190, v174, v56
	v_cvt_pk_bf16_f32 v190, v130, v190
	v_mul_f32_e32 v130, v178, v60
	v_mul_f32_e32 v191, v176, v64
	v_cvt_pk_bf16_f32 v191, v130, v191
	v_add_u32_e32 v130, 3, v187
	global_store_dwordx4 v[192:193], v[188:191], off offset:1024 sc1
	s_cbranch_vccnz .LBB0_119
	v_cmp_gt_i32_e32 vcc, s56, v187
	s_and_saveexec_b64 s[4:5], vcc
	s_xor_b64 s[4:5], exec, s[4:5]
	v_lshlrev_b32_e32 v187, 2, v130
	v_lshrrev_b32_e32 v188, 1, v130
	v_and_b32_e32 v187, 0x80, v187
	v_and_b32_e32 v188, 0x60, v188
	v_and_b32_e32 v130, 0xffffff1f, v130
	v_or3_b32 v130, v187, v130, v188
	s_andn2_saveexec_b64 s[4:5], s[4:5]
	v_cmp_lt_u32_e32 vcc, s54, v130
	s_nop 1
	v_cndmask_b32_e32 v187, v180, v181, vcc
	v_add_lshl_u32 v187, v187, v130, 1
	v_and_b32_e32 v187, 0xffffff00, v187
	v_cndmask_b32_e32 v188, 0, v182, vcc
	v_and_b32_e32 v130, 0x7f, v130
	v_or3_b32 v130, v187, v188, v130
	v_add_u32_e32 v130, 0x1000, v130
	s_or_b64 exec, exec, s[4:5]
.LBB0_119:
	v_and_b32_e32 v187, 0x60, v130
	v_lshlrev_b32_e32 v188, 2, v130
	v_and_or_b32 v187, v188, 16, v187
	v_lshrrev_b32_e32 v188, 1, v130
	v_and_b32_e32 v189, 3, v130
	v_ashrrev_i32_e32 v191, 8, v130
	v_and_or_b32 v190, v188, 12, v189
	v_ashrrev_i32_e32 v188, 31, v191
	v_lshlrev_b32_e32 v130, 6, v130
	v_mul_lo_u32 v194, s36, v188
	v_mov_b64_e32 v[188:189], s[0:1]
	v_and_b32_e32 v130, 0x2000, v130
	v_mad_u64_u32 v[192:193], s[4:5], s36, v191, v[188:189]
	v_lshl_or_b32 v130, v190, 5, v130
	v_mul_f32_e32 v188, v162, v5
	v_mul_f32_e32 v189, v161, v9
	v_lshlrev_b32_e32 v187, 6, v187
	v_mul_i32_i24_e32 v195, s37, v191
	v_cvt_pk_bf16_f32 v188, v188, v189
	v_mul_f32_e32 v189, v164, v13
	v_mul_f32_e32 v190, v163, v17
	v_or3_b32 v130, v130, v187, v179
	v_add3_u32 v193, v195, v193, v194
	v_cvt_pk_bf16_f32 v189, v189, v190
	v_mul_f32_e32 v190, v166, v21
	v_mul_f32_e32 v191, v165, v25
	v_lshlrev_b32_e32 v130, 1, v130
	v_cvt_pk_bf16_f32 v190, v190, v191
	v_mul_f32_e32 v191, v168, v29
	v_lshl_add_u64 v[192:193], v[192:193], 0, v[130:131]
	v_mul_f32_e32 v130, v171, v37
	v_mul_f32_e32 v187, v170, v41
	v_mul_f32_e32 v194, v167, v33
	v_cvt_pk_bf16_f32 v191, v191, v194
	global_store_dwordx4 v[192:193], v[188:191], off sc1
	s_andn2_b64 vcc, exec, s[30:31]
	s_nop 0
	v_cvt_pk_bf16_f32 v188, v130, v187
	v_mul_f32_e32 v130, v173, v45
	v_mul_f32_e32 v187, v172, v49
	v_cvt_pk_bf16_f32 v189, v130, v187
	v_mul_f32_e32 v130, v175, v53
	v_mul_f32_e32 v187, v174, v57
	v_cvt_pk_bf16_f32 v190, v130, v187
	v_mul_f32_e32 v130, v178, v61
	v_mul_f32_e32 v187, v176, v65
	v_cvt_pk_bf16_f32 v191, v130, v187
	global_store_dwordx4 v[192:193], v[188:191], off offset:1024 sc1
	s_cbranch_vccnz .LBB0_57
	v_mov_b64_e32 v[62:63], v[126:127]
	v_mov_b64_e32 v[58:59], v[118:119]
	v_mov_b64_e32 v[54:55], v[122:123]
	v_mov_b64_e32 v[50:51], v[110:111]
	v_mov_b64_e32 v[46:47], v[114:115]
	v_mov_b64_e32 v[42:43], v[102:103]
	v_mov_b64_e32 v[38:39], v[106:107]
	v_mov_b64_e32 v[34:35], v[94:95]
	v_mov_b64_e32 v[30:31], v[98:99]
	v_mov_b64_e32 v[26:27], v[86:87]
	v_mov_b64_e32 v[22:23], v[90:91]
	v_mov_b64_e32 v[18:19], v[78:79]
	v_mov_b64_e32 v[14:15], v[82:83]
	v_mov_b64_e32 v[10:11], v[70:71]
	v_mov_b64_e32 v[6:7], v[74:75]
	v_mov_b64_e32 v[2:3], v[66:67]
	v_mov_b64_e32 v[64:65], v[128:129]
	v_mov_b64_e32 v[60:61], v[120:121]
	v_mov_b64_e32 v[56:57], v[124:125]
	v_mov_b64_e32 v[52:53], v[112:113]
	v_mov_b64_e32 v[48:49], v[116:117]
	v_mov_b64_e32 v[44:45], v[104:105]
	v_mov_b64_e32 v[40:41], v[108:109]
	v_mov_b64_e32 v[36:37], v[96:97]
	v_mov_b64_e32 v[32:33], v[100:101]
	v_mov_b64_e32 v[28:29], v[88:89]
	v_mov_b64_e32 v[24:25], v[92:93]
	v_mov_b64_e32 v[20:21], v[80:81]
	v_mov_b64_e32 v[16:17], v[84:85]
	v_mov_b64_e32 v[12:13], v[72:73]
	v_mov_b64_e32 v[8:9], v[76:77]
	v_mov_b64_e32 v[4:5], v[68:69]
	s_mov_b64 s[0:1], s[34:35]
	s_mov_b32 s3, s58
	s_mov_b32 s23, s40
	v_mov_b32_e32 v162, v132
	v_mov_b32_e32 v161, v133
	v_mov_b32_e32 v164, v134
	v_mov_b32_e32 v163, v135
	v_mov_b32_e32 v166, v136
	v_mov_b32_e32 v165, v137
	v_mov_b32_e32 v168, v183
	v_mov_b32_e32 v167, v184
	v_mov_b32_e32 v171, v138
	v_mov_b32_e32 v170, v139
	v_mov_b32_e32 v173, v140
	v_mov_b32_e32 v172, v141
	v_mov_b32_e32 v175, v142
	v_mov_b32_e32 v174, v143
	v_mov_b32_e32 v178, v185
	v_mov_b32_e32 v176, v186
	s_branch .LBB0_57
